# phase 2 (pool diffs + gMLP gating) rewritten by hand: all loads of an item issued up front
# speedup vs baseline: 1.0010x; 1.0010x over previous
; #define LAS __attribute__((address_space(3)))
; DI u32x2 pk4(f32x4 v) { u32x2 r; r.x = pk2(v[0], v[1]); r.y = pk2(v[2], v[3]); return r; }
; DI int lane_id() { int l = __builtin_amdgcn_mbcnt_hi(-1, __builtin_amdgcn_mbcnt_lo(-1, 0)); asm volatile("" : "+v"(l)); return l; }
; DI void phase2(CP& p, LAS unsigned char* lds, int wid) {
;     const int lane = lane_id(), tid = wid * 64 + lane, fr = lane & 15, fq = lane >> 4;
;     const float* Z = WSF(OFF_Z); bf16_t* DP = WSB(OFF_DP);
;     LAS unsigned char* wm = lds; LAS float* rsl = (LAS float*)(lds + 36864);
;     for (int it = blockIdx.x; it < 256 + 512; it += gridDim.x) {
;         if (it < 256) {
;             const int gt = it * NTHR + tid, c = (gt & 255) * 4, run = gt >> 8, g = c >> 8, win = 2 << g;
;             const int t0 = run * 16, tb = t0 & (SEQ - 1);
;             f32x4 sum = {0.f, 0.f, 0.f, 0.f};
;             for (int j = 1; j < win; ++j) if (tb - j >= 0) sum += *(const f32x4*)(Z + (size_t)(t0 - j) * 1024 + c);
;             for (int i = 0; i < 16; ++i) { const int t = t0 + i, pos = tb + i; const f32x4 zc = *(const f32x4*)(Z + (size_t)t * 1024 + c);
;                 sum += zc; const float cnt = (float)((pos + 1) < win ? (pos + 1) : win); const f32x4 d = sum / cnt - zc;
;                 *(u32x2*)(DP + (size_t)t * 1024 + c) = pk4(d);
;                 if (pos - win + 1 >= 0) sum -= *(const f32x4*)(Z + (size_t)(t - win + 1) * 1024 + c); }
.LBB0_454:
	s_cmp_lt_i32 s34, 3
	s_cselect_b64 s[4:5], -1, 0
	s_and_b64 s[16:17], s[4:5], s[2:3]
	s_andn2_b64 vcc, exec, s[16:17]
	s_cbranch_vccnz .LBB0_471
	s_mov_b64 s[4:5], s[0:1]
	s_mov_b32 s19, 0
	v_mbcnt_hi_u32_b32 v2, -1, v254
	s_cmpk_gt_i32 s6, 0x2ff
	s_cbranch_scc1 .LBB0_471
	s_load_dwordx2 s[8:9], s[4:5], 0xa8
	s_load_dwordx4 s[12:15], s[4:5], 0x28
	s_load_dwordx2 s[22:23], s[4:5], 0x38
	v_mov_b32_e32 v0, v2
	v_mov_b32_e32 v1, 0
	s_and_b32 s2, s88, 0xffffffc0
	v_add_u32_e32 v2, s2, v0
	v_and_b32_e32 v5, 15, v0
	v_lshrrev_b32_e32 v6, 4, v0
	v_and_b32_e32 v3, 0xff, v2
	v_lshlrev_b32_e32 v4, 3, v3
	v_lshlrev_b32_e32 v3, 4, v3
	v_lshlrev_b32_e32 v8, 7, v2
	v_bfe_u32 v9, v2, 1, 1
	v_lshrrev_b32_e32 v7, 8, v2
	v_cmp_le_u32_e32 vcc, v9, v7
	s_nop 1
	v_cndmask_b32_e64 v10, 0, 1.0, vcc
	v_mov_b32_e32 v11, v10
	v_and_b32_e32 v9, 3, v2
	v_lshlrev_b32_e32 v12, 7, v9
	v_add_u32_e32 v12, 0x9000, v12
	v_lshrrev_b32_e32 v7, 2, v2
	v_mul_u32_u24_e32 v13, 0x110, v7
	v_lshl_add_u32 v13, v9, 6, v13
	s_lshl_b32 s3, s33, 4
	v_add_u32_e32 v7, s3, v5
	v_lshlrev_b32_e32 v14, 14, v7
	v_lshl_add_u32 v14, v6, 4, v14
	v_lshl_add_u32 v7, v6, 2, s3
	v_lshlrev_b32_e32 v15, 2, v7
	v_lshlrev_b32_e32 v16, 2, v5
	v_lshlrev_b32_e32 v17, 11, v5
	v_lshl_add_u32 v17, v7, 1, v17
	v_lshlrev_b32_e32 v18, 12, v5
	v_lshl_add_u32 v18, v7, 1, v18
	v_mul_u32_u24_e32 v19, 0x110, v5
	v_lshl_add_u32 v19, v6, 4, v19
	v_and_b32_e32 v20, 0x7f, v2
	v_lshlrev_b32_e32 v20, 2, v20
	v_add_u32_e32 v21, 0x9000, v20
	v_mov_b32_e32 v23, 0x358637bd
	s_waitcnt lgkmcnt(0)
	s_add_u32 s24, s8, 0xf000000
	s_addc_u32 s25, s9, 0
	s_add_u32 s26, s8, 0x11000000
	s_addc_u32 s27, s9, 0
	s_add_u32 s28, s8, 0xe000000
	s_addc_u32 s29, s9, 0
	s_add_u32 s30, s8, 0xd000000
	s_addc_u32 s31, s9, 0
	s_add_u32 s36, s8, 0x12000000
	s_addc_u32 s37, s9, 0
	s_add_u32 s20, s8, 0xcd08000
	s_addc_u32 s21, s9, 0
	s_mov_b32 s39, s6
.Lp2_item:
	s_cmpk_gt_i32 s39, 0xff
	s_cbranch_scc1 .Lp2_gmlp
	s_lshr_b32 s2, s33, 2
	s_lshl_b32 s3, s39, 1
	s_add_i32 s2, s2, s3
	s_lshl_b32 s2, s2, 4
	s_and_b32 s3, s2, 0xfff
	s_and_b32 s4, s33, 3
	s_lshl_b32 s5, 2, s4
	s_lshl_b32 s10, s2, 12
	s_add_u32 s10, s24, s10
	s_addc_u32 s11, s25, 0
	s_add_u32 s10, s10, 0x1000
	s_addc_u32 s11, s11, 0
	s_add_i32 s18, s5, -1
	s_lshl_b32 s18, s18, 12
	s_sub_u32 s8, s10, s18
	s_subb_u32 s9, s11, 0
	global_load_dwordx4 v[164:167], v3, s[8:9] offset:-4096
	global_load_dwordx4 v[168:171], v3, s[8:9]
	s_add_u32 s8, s8, 0x2000
	s_addc_u32 s9, s9, 0
	global_load_dwordx4 v[172:175], v3, s[8:9] offset:-4096
	global_load_dwordx4 v[176:179], v3, s[8:9]
	s_add_u32 s8, s8, 0x2000
	s_addc_u32 s9, s9, 0
	global_load_dwordx4 v[180:183], v3, s[8:9] offset:-4096
	global_load_dwordx4 v[184:187], v3, s[8:9]
	s_add_u32 s8, s8, 0x2000
	s_addc_u32 s9, s9, 0
	global_load_dwordx4 v[188:191], v3, s[8:9] offset:-4096
	global_load_dwordx4 v[192:195], v3, s[8:9]
	s_add_u32 s8, s8, 0x2000
	s_addc_u32 s9, s9, 0
	global_load_dwordx4 v[196:199], v3, s[8:9] offset:-4096
	global_load_dwordx4 v[200:203], v3, s[8:9]
	s_add_u32 s8, s8, 0x2000
	s_addc_u32 s9, s9, 0
	global_load_dwordx4 v[204:207], v3, s[8:9] offset:-4096
	global_load_dwordx4 v[208:211], v3, s[8:9]
	s_add_u32 s8, s8, 0x2000
	s_addc_u32 s9, s9, 0
	global_load_dwordx4 v[212:215], v3, s[8:9] offset:-4096
	global_load_dwordx4 v[216:219], v3, s[8:9]
	s_add_u32 s8, s8, 0x2000
	s_addc_u32 s9, s9, 0
	global_load_dwordx4 v[220:223], v3, s[8:9] offset:-4096
	global_load_dwordx4 v[224:227], v3, s[8:9]
	global_load_dwordx4 v[100:103], v3, s[10:11] offset:-4096
	global_load_dwordx4 v[104:107], v3, s[10:11]
	s_add_u32 s10, s10, 0x2000
	s_addc_u32 s11, s11, 0
	global_load_dwordx4 v[108:111], v3, s[10:11] offset:-4096
	global_load_dwordx4 v[112:115], v3, s[10:11]
	s_add_u32 s10, s10, 0x2000
	s_addc_u32 s11, s11, 0
	global_load_dwordx4 v[116:119], v3, s[10:11] offset:-4096
	global_load_dwordx4 v[120:123], v3, s[10:11]
	s_add_u32 s10, s10, 0x2000
	s_addc_u32 s11, s11, 0
	global_load_dwordx4 v[124:127], v3, s[10:11] offset:-4096
	global_load_dwordx4 v[128:131], v3, s[10:11]
	s_add_u32 s10, s10, 0x2000
	s_addc_u32 s11, s11, 0
	global_load_dwordx4 v[132:135], v3, s[10:11] offset:-4096
	global_load_dwordx4 v[136:139], v3, s[10:11]
	s_add_u32 s10, s10, 0x2000
	s_addc_u32 s11, s11, 0
	global_load_dwordx4 v[140:143], v3, s[10:11] offset:-4096
	global_load_dwordx4 v[144:147], v3, s[10:11]
	s_add_u32 s10, s10, 0x2000
	s_addc_u32 s11, s11, 0
	global_load_dwordx4 v[148:151], v3, s[10:11] offset:-4096
	global_load_dwordx4 v[152:155], v3, s[10:11]
	s_add_u32 s10, s10, 0x2000
	s_addc_u32 s11, s11, 0
	global_load_dwordx4 v[156:159], v3, s[10:11] offset:-4096
	global_load_dwordx4 v[160:163], v3, s[10:11]
	s_lshl_b32 s10, s2, 11
	s_add_u32 s10, s26, s10
	s_addc_u32 s11, s27, 0
	s_add_u32 s10, s10, 0x1000
	s_addc_u32 s11, s11, 0
	v_mov_b32_e32 v24, 0
	v_mov_b32_e32 v25, 0
	v_mov_b32_e32 v26, 0
	v_mov_b32_e32 v27, 0
	s_cmp_eq_u32 s3, 0
	s_cbranch_scc1 .Lp2_pool_slow
	s_sub_i32 s18, 0x7e, s4
	s_lshl_b32 s18, s18, 23
	v_mov_b32_e32 v28, s18
	v_mov_b32_e32 v29, s18
	s_waitcnt vmcnt(31)
	v_pk_add_f32 v[24:25], v[24:25], v[164:165]
	v_pk_add_f32 v[26:27], v[26:27], v[166:167]
	s_cmp_lt_u32 s5, 4
	s_cbranch_scc1 .Lp2_pf_main
	s_waitcnt vmcnt(29)
	v_pk_add_f32 v[24:25], v[24:25], v[168:169]
	v_pk_add_f32 v[26:27], v[26:27], v[170:171]
	v_pk_add_f32 v[24:25], v[24:25], v[172:173]
	v_pk_add_f32 v[26:27], v[26:27], v[174:175]
	s_cmp_lt_u32 s5, 8
	s_cbranch_scc1 .Lp2_pf_main
	s_waitcnt vmcnt(25)
	v_pk_add_f32 v[24:25], v[24:25], v[176:177]
	v_pk_add_f32 v[26:27], v[26:27], v[178:179]
	v_pk_add_f32 v[24:25], v[24:25], v[180:181]
	v_pk_add_f32 v[26:27], v[26:27], v[182:183]
	v_pk_add_f32 v[24:25], v[24:25], v[184:185]
	v_pk_add_f32 v[26:27], v[26:27], v[186:187]
	v_pk_add_f32 v[24:25], v[24:25], v[188:189]
	v_pk_add_f32 v[26:27], v[26:27], v[190:191]
	s_cmp_lt_u32 s5, 16
	s_cbranch_scc1 .Lp2_pf_main
	s_waitcnt vmcnt(17)
	v_pk_add_f32 v[24:25], v[24:25], v[192:193]
	v_pk_add_f32 v[26:27], v[26:27], v[194:195]
	v_pk_add_f32 v[24:25], v[24:25], v[196:197]
	v_pk_add_f32 v[26:27], v[26:27], v[198:199]
	v_pk_add_f32 v[24:25], v[24:25], v[200:201]
	v_pk_add_f32 v[26:27], v[26:27], v[202:203]
	v_pk_add_f32 v[24:25], v[24:25], v[204:205]
	v_pk_add_f32 v[26:27], v[26:27], v[206:207]
	v_pk_add_f32 v[24:25], v[24:25], v[208:209]
	v_pk_add_f32 v[26:27], v[26:27], v[210:211]
	v_pk_add_f32 v[24:25], v[24:25], v[212:213]
	v_pk_add_f32 v[26:27], v[26:27], v[214:215]
	v_pk_add_f32 v[24:25], v[24:25], v[216:217]
	v_pk_add_f32 v[26:27], v[26:27], v[218:219]
	v_pk_add_f32 v[24:25], v[24:25], v[220:221]
	v_pk_add_f32 v[26:27], v[26:27], v[222:223]
; DI u32x2 pk4(f32x4 v) { u32x2 r; r.x = pk2(v[0], v[1]); r.y = pk2(v[2], v[3]); return r; }
; DI void phase2(CP& p, LAS unsigned char* lds, int wid) {
;     ...
;             for (int i = 0; i < 16; ++i) { const int t = t0 + i, pos = tb + i; const f32x4 zc = *(const f32x4*)(Z + (size_t)t * 1024 + c);
;                 sum += zc; const float cnt = (float)((pos + 1) < win ? (pos + 1) : win); const f32x4 d = sum / cnt - zc;
;                 *(u32x2*)(DP + (size_t)t * 1024 + c) = pk4(d);
;                 if (pos - win + 1 >= 0) sum -= *(const f32x4*)(Z + (size_t)(t - win + 1) * 1024 + c); }
.Lp2_pf_main:
	s_waitcnt vmcnt(15)
	v_pk_add_f32 v[24:25], v[24:25], v[100:101]
	v_pk_add_f32 v[26:27], v[26:27], v[102:103]
	v_pk_mul_f32 v[30:31], v[24:25], v[28:29]
	v_pk_mul_f32 v[32:33], v[26:27], v[28:29]
	v_pk_add_f32 v[30:31], v[30:31], v[100:101] neg_lo:[0,1] neg_hi:[0,1]
	v_pk_add_f32 v[32:33], v[32:33], v[102:103] neg_lo:[0,1] neg_hi:[0,1]
	v_cvt_pk_bf16_f32 v34, v30, v31
	v_cvt_pk_bf16_f32 v35, v32, v33
	global_store_dwordx2 v4, v[34:35], s[10:11] offset:-4096
	v_pk_add_f32 v[24:25], v[24:25], v[164:165] neg_lo:[0,1] neg_hi:[0,1]
	v_pk_add_f32 v[26:27], v[26:27], v[166:167] neg_lo:[0,1] neg_hi:[0,1]
	s_waitcnt vmcnt(15)
	v_pk_add_f32 v[24:25], v[24:25], v[104:105]
	v_pk_add_f32 v[26:27], v[26:27], v[106:107]
	v_pk_mul_f32 v[30:31], v[24:25], v[28:29]
	v_pk_mul_f32 v[32:33], v[26:27], v[28:29]
	v_pk_add_f32 v[30:31], v[30:31], v[104:105] neg_lo:[0,1] neg_hi:[0,1]
	v_pk_add_f32 v[32:33], v[32:33], v[106:107] neg_lo:[0,1] neg_hi:[0,1]
	v_cvt_pk_bf16_f32 v36, v30, v31
	v_cvt_pk_bf16_f32 v37, v32, v33
	global_store_dwordx2 v4, v[36:37], s[10:11] offset:-2048
	v_pk_add_f32 v[24:25], v[24:25], v[168:169] neg_lo:[0,1] neg_hi:[0,1]
	v_pk_add_f32 v[26:27], v[26:27], v[170:171] neg_lo:[0,1] neg_hi:[0,1]
	s_waitcnt vmcnt(15)
	v_pk_add_f32 v[24:25], v[24:25], v[108:109]
	v_pk_add_f32 v[26:27], v[26:27], v[110:111]
	v_pk_mul_f32 v[30:31], v[24:25], v[28:29]
	v_pk_mul_f32 v[32:33], v[26:27], v[28:29]
	v_pk_add_f32 v[30:31], v[30:31], v[108:109] neg_lo:[0,1] neg_hi:[0,1]
	v_pk_add_f32 v[32:33], v[32:33], v[110:111] neg_lo:[0,1] neg_hi:[0,1]
	v_cvt_pk_bf16_f32 v34, v30, v31
	v_cvt_pk_bf16_f32 v35, v32, v33
	global_store_dwordx2 v4, v[34:35], s[10:11]
	v_pk_add_f32 v[24:25], v[24:25], v[172:173] neg_lo:[0,1] neg_hi:[0,1]
	v_pk_add_f32 v[26:27], v[26:27], v[174:175] neg_lo:[0,1] neg_hi:[0,1]
	s_waitcnt vmcnt(15)
	v_pk_add_f32 v[24:25], v[24:25], v[112:113]
	v_pk_add_f32 v[26:27], v[26:27], v[114:115]
	v_pk_mul_f32 v[30:31], v[24:25], v[28:29]
	v_pk_mul_f32 v[32:33], v[26:27], v[28:29]
	v_pk_add_f32 v[30:31], v[30:31], v[112:113] neg_lo:[0,1] neg_hi:[0,1]
	v_pk_add_f32 v[32:33], v[32:33], v[114:115] neg_lo:[0,1] neg_hi:[0,1]
	v_cvt_pk_bf16_f32 v36, v30, v31
	v_cvt_pk_bf16_f32 v37, v32, v33
	global_store_dwordx2 v4, v[36:37], s[10:11] offset:2048
	v_pk_add_f32 v[24:25], v[24:25], v[176:177] neg_lo:[0,1] neg_hi:[0,1]
	v_pk_add_f32 v[26:27], v[26:27], v[178:179] neg_lo:[0,1] neg_hi:[0,1]
	s_waitcnt vmcnt(15)
	v_pk_add_f32 v[24:25], v[24:25], v[116:117]
	v_pk_add_f32 v[26:27], v[26:27], v[118:119]
	v_pk_mul_f32 v[30:31], v[24:25], v[28:29]
	v_pk_mul_f32 v[32:33], v[26:27], v[28:29]
	v_pk_add_f32 v[30:31], v[30:31], v[116:117] neg_lo:[0,1] neg_hi:[0,1]
	v_pk_add_f32 v[32:33], v[32:33], v[118:119] neg_lo:[0,1] neg_hi:[0,1]
	v_cvt_pk_bf16_f32 v34, v30, v31
	v_cvt_pk_bf16_f32 v35, v32, v33
	s_add_u32 s10, s10, 0x2000
	s_addc_u32 s11, s11, 0
	global_store_dwordx2 v4, v[34:35], s[10:11] offset:-4096
	v_pk_add_f32 v[24:25], v[24:25], v[180:181] neg_lo:[0,1] neg_hi:[0,1]
	v_pk_add_f32 v[26:27], v[26:27], v[182:183] neg_lo:[0,1] neg_hi:[0,1]
	s_waitcnt vmcnt(15)
	v_pk_add_f32 v[24:25], v[24:25], v[120:121]
	v_pk_add_f32 v[26:27], v[26:27], v[122:123]
	v_pk_mul_f32 v[30:31], v[24:25], v[28:29]
	v_pk_mul_f32 v[32:33], v[26:27], v[28:29]
	v_pk_add_f32 v[30:31], v[30:31], v[120:121] neg_lo:[0,1] neg_hi:[0,1]
	v_pk_add_f32 v[32:33], v[32:33], v[122:123] neg_lo:[0,1] neg_hi:[0,1]
	v_cvt_pk_bf16_f32 v36, v30, v31
	v_cvt_pk_bf16_f32 v37, v32, v33
	global_store_dwordx2 v4, v[36:37], s[10:11] offset:-2048
	v_pk_add_f32 v[24:25], v[24:25], v[184:185] neg_lo:[0,1] neg_hi:[0,1]
	v_pk_add_f32 v[26:27], v[26:27], v[186:187] neg_lo:[0,1] neg_hi:[0,1]
	s_waitcnt vmcnt(15)
	v_pk_add_f32 v[24:25], v[24:25], v[124:125]
	v_pk_add_f32 v[26:27], v[26:27], v[126:127]
	v_pk_mul_f32 v[30:31], v[24:25], v[28:29]
	v_pk_mul_f32 v[32:33], v[26:27], v[28:29]
	v_pk_add_f32 v[30:31], v[30:31], v[124:125] neg_lo:[0,1] neg_hi:[0,1]
	v_pk_add_f32 v[32:33], v[32:33], v[126:127] neg_lo:[0,1] neg_hi:[0,1]
	v_cvt_pk_bf16_f32 v34, v30, v31
	v_cvt_pk_bf16_f32 v35, v32, v33
	global_store_dwordx2 v4, v[34:35], s[10:11]
	v_pk_add_f32 v[24:25], v[24:25], v[188:189] neg_lo:[0,1] neg_hi:[0,1]
	v_pk_add_f32 v[26:27], v[26:27], v[190:191] neg_lo:[0,1] neg_hi:[0,1]
	s_waitcnt vmcnt(15)
	v_pk_add_f32 v[24:25], v[24:25], v[128:129]
	v_pk_add_f32 v[26:27], v[26:27], v[130:131]
	v_pk_mul_f32 v[30:31], v[24:25], v[28:29]
	v_pk_mul_f32 v[32:33], v[26:27], v[28:29]
	v_pk_add_f32 v[30:31], v[30:31], v[128:129] neg_lo:[0,1] neg_hi:[0,1]
	v_pk_add_f32 v[32:33], v[32:33], v[130:131] neg_lo:[0,1] neg_hi:[0,1]
	v_cvt_pk_bf16_f32 v36, v30, v31
	v_cvt_pk_bf16_f32 v37, v32, v33
	global_store_dwordx2 v4, v[36:37], s[10:11] offset:2048
	v_pk_add_f32 v[24:25], v[24:25], v[192:193] neg_lo:[0,1] neg_hi:[0,1]
	v_pk_add_f32 v[26:27], v[26:27], v[194:195] neg_lo:[0,1] neg_hi:[0,1]
	s_waitcnt vmcnt(15)
	v_pk_add_f32 v[24:25], v[24:25], v[132:133]
	v_pk_add_f32 v[26:27], v[26:27], v[134:135]
	v_pk_mul_f32 v[30:31], v[24:25], v[28:29]
	v_pk_mul_f32 v[32:33], v[26:27], v[28:29]
	v_pk_add_f32 v[30:31], v[30:31], v[132:133] neg_lo:[0,1] neg_hi:[0,1]
	v_pk_add_f32 v[32:33], v[32:33], v[134:135] neg_lo:[0,1] neg_hi:[0,1]
	v_cvt_pk_bf16_f32 v34, v30, v31
	v_cvt_pk_bf16_f32 v35, v32, v33
	s_add_u32 s10, s10, 0x2000
	s_addc_u32 s11, s11, 0
	global_store_dwordx2 v4, v[34:35], s[10:11] offset:-4096
	v_pk_add_f32 v[24:25], v[24:25], v[196:197] neg_lo:[0,1] neg_hi:[0,1]
	v_pk_add_f32 v[26:27], v[26:27], v[198:199] neg_lo:[0,1] neg_hi:[0,1]
	s_waitcnt vmcnt(15)
; DI u32x2 pk4(f32x4 v) { u32x2 r; r.x = pk2(v[0], v[1]); r.y = pk2(v[2], v[3]); return r; }
; DI void phase2(CP& p, LAS unsigned char* lds, int wid) {
;     ...
;             for (int i = 0; i < 16; ++i) { const int t = t0 + i, pos = tb + i; const f32x4 zc = *(const f32x4*)(Z + (size_t)t * 1024 + c);
;                 sum += zc; const float cnt = (float)((pos + 1) < win ? (pos + 1) : win); const f32x4 d = sum / cnt - zc;
;                 *(u32x2*)(DP + (size_t)t * 1024 + c) = pk4(d);
;                 if (pos - win + 1 >= 0) sum -= *(const f32x4*)(Z + (size_t)(t - win + 1) * 1024 + c); }
	v_pk_add_f32 v[24:25], v[24:25], v[136:137]
	v_pk_add_f32 v[26:27], v[26:27], v[138:139]
	v_pk_mul_f32 v[30:31], v[24:25], v[28:29]
	v_pk_mul_f32 v[32:33], v[26:27], v[28:29]
	v_pk_add_f32 v[30:31], v[30:31], v[136:137] neg_lo:[0,1] neg_hi:[0,1]
	v_pk_add_f32 v[32:33], v[32:33], v[138:139] neg_lo:[0,1] neg_hi:[0,1]
	v_cvt_pk_bf16_f32 v36, v30, v31
	v_cvt_pk_bf16_f32 v37, v32, v33
	global_store_dwordx2 v4, v[36:37], s[10:11] offset:-2048
	v_pk_add_f32 v[24:25], v[24:25], v[200:201] neg_lo:[0,1] neg_hi:[0,1]
	v_pk_add_f32 v[26:27], v[26:27], v[202:203] neg_lo:[0,1] neg_hi:[0,1]
	s_waitcnt vmcnt(15)
	v_pk_add_f32 v[24:25], v[24:25], v[140:141]
	v_pk_add_f32 v[26:27], v[26:27], v[142:143]
	v_pk_mul_f32 v[30:31], v[24:25], v[28:29]
	v_pk_mul_f32 v[32:33], v[26:27], v[28:29]
	v_pk_add_f32 v[30:31], v[30:31], v[140:141] neg_lo:[0,1] neg_hi:[0,1]
	v_pk_add_f32 v[32:33], v[32:33], v[142:143] neg_lo:[0,1] neg_hi:[0,1]
	v_cvt_pk_bf16_f32 v34, v30, v31
	v_cvt_pk_bf16_f32 v35, v32, v33
	global_store_dwordx2 v4, v[34:35], s[10:11]
	v_pk_add_f32 v[24:25], v[24:25], v[204:205] neg_lo:[0,1] neg_hi:[0,1]
	v_pk_add_f32 v[26:27], v[26:27], v[206:207] neg_lo:[0,1] neg_hi:[0,1]
	s_waitcnt vmcnt(15)
	v_pk_add_f32 v[24:25], v[24:25], v[144:145]
	v_pk_add_f32 v[26:27], v[26:27], v[146:147]
	v_pk_mul_f32 v[30:31], v[24:25], v[28:29]
	v_pk_mul_f32 v[32:33], v[26:27], v[28:29]
	v_pk_add_f32 v[30:31], v[30:31], v[144:145] neg_lo:[0,1] neg_hi:[0,1]
	v_pk_add_f32 v[32:33], v[32:33], v[146:147] neg_lo:[0,1] neg_hi:[0,1]
	v_cvt_pk_bf16_f32 v36, v30, v31
	v_cvt_pk_bf16_f32 v37, v32, v33
	global_store_dwordx2 v4, v[36:37], s[10:11] offset:2048
	v_pk_add_f32 v[24:25], v[24:25], v[208:209] neg_lo:[0,1] neg_hi:[0,1]
	v_pk_add_f32 v[26:27], v[26:27], v[210:211] neg_lo:[0,1] neg_hi:[0,1]
	s_waitcnt vmcnt(15)
	v_pk_add_f32 v[24:25], v[24:25], v[148:149]
	v_pk_add_f32 v[26:27], v[26:27], v[150:151]
	v_pk_mul_f32 v[30:31], v[24:25], v[28:29]
	v_pk_mul_f32 v[32:33], v[26:27], v[28:29]
	v_pk_add_f32 v[30:31], v[30:31], v[148:149] neg_lo:[0,1] neg_hi:[0,1]
	v_pk_add_f32 v[32:33], v[32:33], v[150:151] neg_lo:[0,1] neg_hi:[0,1]
	v_cvt_pk_bf16_f32 v34, v30, v31
	v_cvt_pk_bf16_f32 v35, v32, v33
	s_add_u32 s10, s10, 0x2000
	s_addc_u32 s11, s11, 0
	global_store_dwordx2 v4, v[34:35], s[10:11] offset:-4096
	v_pk_add_f32 v[24:25], v[24:25], v[212:213] neg_lo:[0,1] neg_hi:[0,1]
	v_pk_add_f32 v[26:27], v[26:27], v[214:215] neg_lo:[0,1] neg_hi:[0,1]
	s_waitcnt vmcnt(15)
	v_pk_add_f32 v[24:25], v[24:25], v[152:153]
	v_pk_add_f32 v[26:27], v[26:27], v[154:155]
	v_pk_mul_f32 v[30:31], v[24:25], v[28:29]
	v_pk_mul_f32 v[32:33], v[26:27], v[28:29]
	v_pk_add_f32 v[30:31], v[30:31], v[152:153] neg_lo:[0,1] neg_hi:[0,1]
	v_pk_add_f32 v[32:33], v[32:33], v[154:155] neg_lo:[0,1] neg_hi:[0,1]
	v_cvt_pk_bf16_f32 v36, v30, v31
	v_cvt_pk_bf16_f32 v37, v32, v33
	global_store_dwordx2 v4, v[36:37], s[10:11] offset:-2048
	v_pk_add_f32 v[24:25], v[24:25], v[216:217] neg_lo:[0,1] neg_hi:[0,1]
	v_pk_add_f32 v[26:27], v[26:27], v[218:219] neg_lo:[0,1] neg_hi:[0,1]
	s_waitcnt vmcnt(15)
	v_pk_add_f32 v[24:25], v[24:25], v[156:157]
	v_pk_add_f32 v[26:27], v[26:27], v[158:159]
	v_pk_mul_f32 v[30:31], v[24:25], v[28:29]
	v_pk_mul_f32 v[32:33], v[26:27], v[28:29]
	v_pk_add_f32 v[30:31], v[30:31], v[156:157] neg_lo:[0,1] neg_hi:[0,1]
	v_pk_add_f32 v[32:33], v[32:33], v[158:159] neg_lo:[0,1] neg_hi:[0,1]
	v_cvt_pk_bf16_f32 v34, v30, v31
	v_cvt_pk_bf16_f32 v35, v32, v33
	global_store_dwordx2 v4, v[34:35], s[10:11]
	v_pk_add_f32 v[24:25], v[24:25], v[220:221] neg_lo:[0,1] neg_hi:[0,1]
	v_pk_add_f32 v[26:27], v[26:27], v[222:223] neg_lo:[0,1] neg_hi:[0,1]
	s_waitcnt vmcnt(15)
	v_pk_add_f32 v[24:25], v[24:25], v[160:161]
	v_pk_add_f32 v[26:27], v[26:27], v[162:163]
	v_pk_mul_f32 v[30:31], v[24:25], v[28:29]
	v_pk_mul_f32 v[32:33], v[26:27], v[28:29]
	v_pk_add_f32 v[30:31], v[30:31], v[160:161] neg_lo:[0,1] neg_hi:[0,1]
	v_pk_add_f32 v[32:33], v[32:33], v[162:163] neg_lo:[0,1] neg_hi:[0,1]
	v_cvt_pk_bf16_f32 v36, v30, v31
	v_cvt_pk_bf16_f32 v37, v32, v33
	global_store_dwordx2 v4, v[36:37], s[10:11] offset:2048
	v_pk_add_f32 v[24:25], v[24:25], v[224:225] neg_lo:[0,1] neg_hi:[0,1]
	v_pk_add_f32 v[26:27], v[26:27], v[226:227] neg_lo:[0,1] neg_hi:[0,1]
	s_branch .Lp2_next
.Lp2_pool_slow:
	s_waitcnt vmcnt(0)
	s_min_u32 s18, s5, 1
	v_cvt_f32_u32_e32 v28, s18
	v_rcp_f32_e32 v29, v28
	v_pk_add_f32 v[24:25], v[24:25], v[100:101]
	v_pk_add_f32 v[26:27], v[26:27], v[102:103]
	v_fma_f32 v30, -v28, v29, 1.0
	v_fmac_f32_e32 v29, v30, v29
	v_mul_f32_e32 v30, v24, v29
	v_fma_f32 v31, -v28, v30, v24
	v_fmac_f32_e32 v30, v31, v29
	v_fma_f32 v31, -v28, v30, v24
	v_fmac_f32_e32 v30, v31, v29
	v_sub_f32_e32 v36, v30, v100
	v_mul_f32_e32 v30, v25, v29
	v_fma_f32 v31, -v28, v30, v25
	v_fmac_f32_e32 v30, v31, v29
	v_fma_f32 v31, -v28, v30, v25
	v_fmac_f32_e32 v30, v31, v29
	v_sub_f32_e32 v37, v30, v101
	v_mul_f32_e32 v30, v26, v29
	v_fma_f32 v31, -v28, v30, v26
	v_fmac_f32_e32 v30, v31, v29
	v_fma_f32 v31, -v28, v30, v26
	v_fmac_f32_e32 v30, v31, v29
	v_sub_f32_e32 v38, v30, v102
	v_mul_f32_e32 v30, v27, v29
	v_fma_f32 v31, -v28, v30, v27
	v_fmac_f32_e32 v30, v31, v29
	v_fma_f32 v31, -v28, v30, v27
	v_fmac_f32_e32 v30, v31, v29
	v_sub_f32_e32 v39, v30, v103
	v_cvt_pk_bf16_f32 v34, v36, v37
	v_cvt_pk_bf16_f32 v35, v38, v39
	s_nop 0
	global_store_dwordx2 v4, v[34:35], s[10:11] offset:-4096
	s_cmp_gt_u32 s5, 1
	s_cbranch_scc1 .Lp2_ps_0
	v_pk_add_f32 v[24:25], v[24:25], v[164:165] neg_lo:[0,1] neg_hi:[0,1]
	v_pk_add_f32 v[26:27], v[26:27], v[166:167] neg_lo:[0,1] neg_hi:[0,1]
; DI u32x2 pk4(f32x4 v) { u32x2 r; r.x = pk2(v[0], v[1]); r.y = pk2(v[2], v[3]); return r; }
; DI void phase2(CP& p, LAS unsigned char* lds, int wid) {
;     ...
;             for (int i = 0; i < 16; ++i) { const int t = t0 + i, pos = tb + i; const f32x4 zc = *(const f32x4*)(Z + (size_t)t * 1024 + c);
;                 sum += zc; const float cnt = (float)((pos + 1) < win ? (pos + 1) : win); const f32x4 d = sum / cnt - zc;
;                 *(u32x2*)(DP + (size_t)t * 1024 + c) = pk4(d);
;                 if (pos - win + 1 >= 0) sum -= *(const f32x4*)(Z + (size_t)(t - win + 1) * 1024 + c); }
.Lp2_ps_0:
	s_min_u32 s18, s5, 2
	v_cvt_f32_u32_e32 v28, s18
	v_rcp_f32_e32 v29, v28
	v_pk_add_f32 v[24:25], v[24:25], v[104:105]
	v_pk_add_f32 v[26:27], v[26:27], v[106:107]
	v_fma_f32 v30, -v28, v29, 1.0
	v_fmac_f32_e32 v29, v30, v29
	v_mul_f32_e32 v30, v24, v29
	v_fma_f32 v31, -v28, v30, v24
	v_fmac_f32_e32 v30, v31, v29
	v_fma_f32 v31, -v28, v30, v24
	v_fmac_f32_e32 v30, v31, v29
	v_sub_f32_e32 v36, v30, v104
	v_mul_f32_e32 v30, v25, v29
	v_fma_f32 v31, -v28, v30, v25
	v_fmac_f32_e32 v30, v31, v29
	v_fma_f32 v31, -v28, v30, v25
	v_fmac_f32_e32 v30, v31, v29
	v_sub_f32_e32 v37, v30, v105
	v_mul_f32_e32 v30, v26, v29
	v_fma_f32 v31, -v28, v30, v26
	v_fmac_f32_e32 v30, v31, v29
	v_fma_f32 v31, -v28, v30, v26
	v_fmac_f32_e32 v30, v31, v29
	v_sub_f32_e32 v38, v30, v106
	v_mul_f32_e32 v30, v27, v29
	v_fma_f32 v31, -v28, v30, v27
	v_fmac_f32_e32 v30, v31, v29
	v_fma_f32 v31, -v28, v30, v27
	v_fmac_f32_e32 v30, v31, v29
	v_sub_f32_e32 v39, v30, v107
	v_cvt_pk_bf16_f32 v34, v36, v37
	v_cvt_pk_bf16_f32 v35, v38, v39
	s_nop 0
	global_store_dwordx2 v4, v[34:35], s[10:11] offset:-2048
	s_cmp_gt_u32 s5, 2
	s_cbranch_scc1 .Lp2_ps_1
	v_pk_add_f32 v[24:25], v[24:25], v[168:169] neg_lo:[0,1] neg_hi:[0,1]
	v_pk_add_f32 v[26:27], v[26:27], v[170:171] neg_lo:[0,1] neg_hi:[0,1]
.Lp2_ps_1:
	s_min_u32 s18, s5, 3
	v_cvt_f32_u32_e32 v28, s18
	v_rcp_f32_e32 v29, v28
	v_pk_add_f32 v[24:25], v[24:25], v[108:109]
	v_pk_add_f32 v[26:27], v[26:27], v[110:111]
	v_fma_f32 v30, -v28, v29, 1.0
	v_fmac_f32_e32 v29, v30, v29
	v_mul_f32_e32 v30, v24, v29
	v_fma_f32 v31, -v28, v30, v24
	v_fmac_f32_e32 v30, v31, v29
	v_fma_f32 v31, -v28, v30, v24
	v_fmac_f32_e32 v30, v31, v29
	v_sub_f32_e32 v36, v30, v108
	v_mul_f32_e32 v30, v25, v29
	v_fma_f32 v31, -v28, v30, v25
	v_fmac_f32_e32 v30, v31, v29
	v_fma_f32 v31, -v28, v30, v25
	v_fmac_f32_e32 v30, v31, v29
	v_sub_f32_e32 v37, v30, v109
	v_mul_f32_e32 v30, v26, v29
	v_fma_f32 v31, -v28, v30, v26
	v_fmac_f32_e32 v30, v31, v29
	v_fma_f32 v31, -v28, v30, v26
	v_fmac_f32_e32 v30, v31, v29
	v_sub_f32_e32 v38, v30, v110
	v_mul_f32_e32 v30, v27, v29
	v_fma_f32 v31, -v28, v30, v27
	v_fmac_f32_e32 v30, v31, v29
	v_fma_f32 v31, -v28, v30, v27
	v_fmac_f32_e32 v30, v31, v29
	v_sub_f32_e32 v39, v30, v111
	v_cvt_pk_bf16_f32 v34, v36, v37
	v_cvt_pk_bf16_f32 v35, v38, v39
	s_nop 0
	global_store_dwordx2 v4, v[34:35], s[10:11]
	s_cmp_gt_u32 s5, 3
	s_cbranch_scc1 .Lp2_ps_2
	v_pk_add_f32 v[24:25], v[24:25], v[172:173] neg_lo:[0,1] neg_hi:[0,1]
	v_pk_add_f32 v[26:27], v[26:27], v[174:175] neg_lo:[0,1] neg_hi:[0,1]
.Lp2_ps_2:
	s_min_u32 s18, s5, 4
	v_cvt_f32_u32_e32 v28, s18
	v_rcp_f32_e32 v29, v28
	v_pk_add_f32 v[24:25], v[24:25], v[112:113]
	v_pk_add_f32 v[26:27], v[26:27], v[114:115]
	v_fma_f32 v30, -v28, v29, 1.0
	v_fmac_f32_e32 v29, v30, v29
	v_mul_f32_e32 v30, v24, v29
	v_fma_f32 v31, -v28, v30, v24
	v_fmac_f32_e32 v30, v31, v29
	v_fma_f32 v31, -v28, v30, v24
	v_fmac_f32_e32 v30, v31, v29
	v_sub_f32_e32 v36, v30, v112
	v_mul_f32_e32 v30, v25, v29
	v_fma_f32 v31, -v28, v30, v25
	v_fmac_f32_e32 v30, v31, v29
	v_fma_f32 v31, -v28, v30, v25
	v_fmac_f32_e32 v30, v31, v29
	v_sub_f32_e32 v37, v30, v113
	v_mul_f32_e32 v30, v26, v29
	v_fma_f32 v31, -v28, v30, v26
	v_fmac_f32_e32 v30, v31, v29
	v_fma_f32 v31, -v28, v30, v26
	v_fmac_f32_e32 v30, v31, v29
	v_sub_f32_e32 v38, v30, v114
	v_mul_f32_e32 v30, v27, v29
	v_fma_f32 v31, -v28, v30, v27
	v_fmac_f32_e32 v30, v31, v29
	v_fma_f32 v31, -v28, v30, v27
	v_fmac_f32_e32 v30, v31, v29
	v_sub_f32_e32 v39, v30, v115
	v_cvt_pk_bf16_f32 v34, v36, v37
	v_cvt_pk_bf16_f32 v35, v38, v39
	s_nop 0
	global_store_dwordx2 v4, v[34:35], s[10:11] offset:2048
	s_cmp_gt_u32 s5, 4
	s_cbranch_scc1 .Lp2_ps_3
	v_pk_add_f32 v[24:25], v[24:25], v[176:177] neg_lo:[0,1] neg_hi:[0,1]
	v_pk_add_f32 v[26:27], v[26:27], v[178:179] neg_lo:[0,1] neg_hi:[0,1]
.Lp2_ps_3:
	s_min_u32 s18, s5, 5
	v_cvt_f32_u32_e32 v28, s18
	v_rcp_f32_e32 v29, v28
	v_pk_add_f32 v[24:25], v[24:25], v[116:117]
	v_pk_add_f32 v[26:27], v[26:27], v[118:119]
	v_fma_f32 v30, -v28, v29, 1.0
	v_fmac_f32_e32 v29, v30, v29
	v_mul_f32_e32 v30, v24, v29
	v_fma_f32 v31, -v28, v30, v24
	v_fmac_f32_e32 v30, v31, v29
	v_fma_f32 v31, -v28, v30, v24
	v_fmac_f32_e32 v30, v31, v29
	v_sub_f32_e32 v36, v30, v116
	v_mul_f32_e32 v30, v25, v29
	v_fma_f32 v31, -v28, v30, v25
	v_fmac_f32_e32 v30, v31, v29
	v_fma_f32 v31, -v28, v30, v25
	v_fmac_f32_e32 v30, v31, v29
	v_sub_f32_e32 v37, v30, v117
	v_mul_f32_e32 v30, v26, v29
	v_fma_f32 v31, -v28, v30, v26
	v_fmac_f32_e32 v30, v31, v29
	v_fma_f32 v31, -v28, v30, v26
	v_fmac_f32_e32 v30, v31, v29
	v_sub_f32_e32 v38, v30, v118
	v_mul_f32_e32 v30, v27, v29
	v_fma_f32 v31, -v28, v30, v27
	v_fmac_f32_e32 v30, v31, v29
	v_fma_f32 v31, -v28, v30, v27
	v_fmac_f32_e32 v30, v31, v29
	v_sub_f32_e32 v39, v30, v119
	v_cvt_pk_bf16_f32 v34, v36, v37
	v_cvt_pk_bf16_f32 v35, v38, v39
	s_add_u32 s10, s10, 0x2000
	s_addc_u32 s11, s11, 0
	s_nop 0
	global_store_dwordx2 v4, v[34:35], s[10:11] offset:-4096
	s_cmp_gt_u32 s5, 5
	s_cbranch_scc1 .Lp2_ps_4
	v_pk_add_f32 v[24:25], v[24:25], v[180:181] neg_lo:[0,1] neg_hi:[0,1]
	v_pk_add_f32 v[26:27], v[26:27], v[182:183] neg_lo:[0,1] neg_hi:[0,1]
; DI u32x2 pk4(f32x4 v) { u32x2 r; r.x = pk2(v[0], v[1]); r.y = pk2(v[2], v[3]); return r; }
; DI void phase2(CP& p, LAS unsigned char* lds, int wid) {
;     ...
;             for (int i = 0; i < 16; ++i) { const int t = t0 + i, pos = tb + i; const f32x4 zc = *(const f32x4*)(Z + (size_t)t * 1024 + c);
;                 sum += zc; const float cnt = (float)((pos + 1) < win ? (pos + 1) : win); const f32x4 d = sum / cnt - zc;
;                 *(u32x2*)(DP + (size_t)t * 1024 + c) = pk4(d);
;                 if (pos - win + 1 >= 0) sum -= *(const f32x4*)(Z + (size_t)(t - win + 1) * 1024 + c); }
.Lp2_ps_4:
	s_min_u32 s18, s5, 6
	v_cvt_f32_u32_e32 v28, s18
	v_rcp_f32_e32 v29, v28
	v_pk_add_f32 v[24:25], v[24:25], v[120:121]
	v_pk_add_f32 v[26:27], v[26:27], v[122:123]
	v_fma_f32 v30, -v28, v29, 1.0
	v_fmac_f32_e32 v29, v30, v29
	v_mul_f32_e32 v30, v24, v29
	v_fma_f32 v31, -v28, v30, v24
	v_fmac_f32_e32 v30, v31, v29
	v_fma_f32 v31, -v28, v30, v24
	v_fmac_f32_e32 v30, v31, v29
	v_sub_f32_e32 v36, v30, v120
	v_mul_f32_e32 v30, v25, v29
	v_fma_f32 v31, -v28, v30, v25
	v_fmac_f32_e32 v30, v31, v29
	v_fma_f32 v31, -v28, v30, v25
	v_fmac_f32_e32 v30, v31, v29
	v_sub_f32_e32 v37, v30, v121
	v_mul_f32_e32 v30, v26, v29
	v_fma_f32 v31, -v28, v30, v26
	v_fmac_f32_e32 v30, v31, v29
	v_fma_f32 v31, -v28, v30, v26
	v_fmac_f32_e32 v30, v31, v29
	v_sub_f32_e32 v38, v30, v122
	v_mul_f32_e32 v30, v27, v29
	v_fma_f32 v31, -v28, v30, v27
	v_fmac_f32_e32 v30, v31, v29
	v_fma_f32 v31, -v28, v30, v27
	v_fmac_f32_e32 v30, v31, v29
	v_sub_f32_e32 v39, v30, v123
	v_cvt_pk_bf16_f32 v34, v36, v37
	v_cvt_pk_bf16_f32 v35, v38, v39
	s_nop 0
	global_store_dwordx2 v4, v[34:35], s[10:11] offset:-2048
	s_cmp_gt_u32 s5, 6
	s_cbranch_scc1 .Lp2_ps_5
	v_pk_add_f32 v[24:25], v[24:25], v[184:185] neg_lo:[0,1] neg_hi:[0,1]
	v_pk_add_f32 v[26:27], v[26:27], v[186:187] neg_lo:[0,1] neg_hi:[0,1]
.Lp2_ps_5:
	s_min_u32 s18, s5, 7
	v_cvt_f32_u32_e32 v28, s18
	v_rcp_f32_e32 v29, v28
	v_pk_add_f32 v[24:25], v[24:25], v[124:125]
	v_pk_add_f32 v[26:27], v[26:27], v[126:127]
	v_fma_f32 v30, -v28, v29, 1.0
	v_fmac_f32_e32 v29, v30, v29
	v_mul_f32_e32 v30, v24, v29
	v_fma_f32 v31, -v28, v30, v24
	v_fmac_f32_e32 v30, v31, v29
	v_fma_f32 v31, -v28, v30, v24
	v_fmac_f32_e32 v30, v31, v29
	v_sub_f32_e32 v36, v30, v124
	v_mul_f32_e32 v30, v25, v29
	v_fma_f32 v31, -v28, v30, v25
	v_fmac_f32_e32 v30, v31, v29
	v_fma_f32 v31, -v28, v30, v25
	v_fmac_f32_e32 v30, v31, v29
	v_sub_f32_e32 v37, v30, v125
	v_mul_f32_e32 v30, v26, v29
	v_fma_f32 v31, -v28, v30, v26
	v_fmac_f32_e32 v30, v31, v29
	v_fma_f32 v31, -v28, v30, v26
	v_fmac_f32_e32 v30, v31, v29
	v_sub_f32_e32 v38, v30, v126
	v_mul_f32_e32 v30, v27, v29
	v_fma_f32 v31, -v28, v30, v27
	v_fmac_f32_e32 v30, v31, v29
	v_fma_f32 v31, -v28, v30, v27
	v_fmac_f32_e32 v30, v31, v29
	v_sub_f32_e32 v39, v30, v127
	v_cvt_pk_bf16_f32 v34, v36, v37
	v_cvt_pk_bf16_f32 v35, v38, v39
	s_nop 0
	global_store_dwordx2 v4, v[34:35], s[10:11]
	s_cmp_gt_u32 s5, 7
	s_cbranch_scc1 .Lp2_ps_6
	v_pk_add_f32 v[24:25], v[24:25], v[188:189] neg_lo:[0,1] neg_hi:[0,1]
	v_pk_add_f32 v[26:27], v[26:27], v[190:191] neg_lo:[0,1] neg_hi:[0,1]
.Lp2_ps_6:
	s_min_u32 s18, s5, 8
	v_cvt_f32_u32_e32 v28, s18
	v_rcp_f32_e32 v29, v28
	v_pk_add_f32 v[24:25], v[24:25], v[128:129]
	v_pk_add_f32 v[26:27], v[26:27], v[130:131]
	v_fma_f32 v30, -v28, v29, 1.0
	v_fmac_f32_e32 v29, v30, v29
	v_mul_f32_e32 v30, v24, v29
	v_fma_f32 v31, -v28, v30, v24
	v_fmac_f32_e32 v30, v31, v29
	v_fma_f32 v31, -v28, v30, v24
	v_fmac_f32_e32 v30, v31, v29
	v_sub_f32_e32 v36, v30, v128
	v_mul_f32_e32 v30, v25, v29
	v_fma_f32 v31, -v28, v30, v25
	v_fmac_f32_e32 v30, v31, v29
	v_fma_f32 v31, -v28, v30, v25
	v_fmac_f32_e32 v30, v31, v29
	v_sub_f32_e32 v37, v30, v129
	v_mul_f32_e32 v30, v26, v29
	v_fma_f32 v31, -v28, v30, v26
	v_fmac_f32_e32 v30, v31, v29
	v_fma_f32 v31, -v28, v30, v26
	v_fmac_f32_e32 v30, v31, v29
	v_sub_f32_e32 v38, v30, v130
	v_mul_f32_e32 v30, v27, v29
	v_fma_f32 v31, -v28, v30, v27
	v_fmac_f32_e32 v30, v31, v29
	v_fma_f32 v31, -v28, v30, v27
	v_fmac_f32_e32 v30, v31, v29
	v_sub_f32_e32 v39, v30, v131
	v_cvt_pk_bf16_f32 v34, v36, v37
	v_cvt_pk_bf16_f32 v35, v38, v39
	s_nop 0
	global_store_dwordx2 v4, v[34:35], s[10:11] offset:2048
	s_cmp_gt_u32 s5, 8
	s_cbranch_scc1 .Lp2_ps_7
	v_pk_add_f32 v[24:25], v[24:25], v[192:193] neg_lo:[0,1] neg_hi:[0,1]
	v_pk_add_f32 v[26:27], v[26:27], v[194:195] neg_lo:[0,1] neg_hi:[0,1]
.Lp2_ps_7:
	s_min_u32 s18, s5, 9
	v_cvt_f32_u32_e32 v28, s18
	v_rcp_f32_e32 v29, v28
	v_pk_add_f32 v[24:25], v[24:25], v[132:133]
	v_pk_add_f32 v[26:27], v[26:27], v[134:135]
	v_fma_f32 v30, -v28, v29, 1.0
	v_fmac_f32_e32 v29, v30, v29
	v_mul_f32_e32 v30, v24, v29
	v_fma_f32 v31, -v28, v30, v24
	v_fmac_f32_e32 v30, v31, v29
	v_fma_f32 v31, -v28, v30, v24
	v_fmac_f32_e32 v30, v31, v29
	v_sub_f32_e32 v36, v30, v132
	v_mul_f32_e32 v30, v25, v29
	v_fma_f32 v31, -v28, v30, v25
	v_fmac_f32_e32 v30, v31, v29
	v_fma_f32 v31, -v28, v30, v25
	v_fmac_f32_e32 v30, v31, v29
	v_sub_f32_e32 v37, v30, v133
	v_mul_f32_e32 v30, v26, v29
	v_fma_f32 v31, -v28, v30, v26
	v_fmac_f32_e32 v30, v31, v29
	v_fma_f32 v31, -v28, v30, v26
	v_fmac_f32_e32 v30, v31, v29
	v_sub_f32_e32 v38, v30, v134
	v_mul_f32_e32 v30, v27, v29
	v_fma_f32 v31, -v28, v30, v27
	v_fmac_f32_e32 v30, v31, v29
	v_fma_f32 v31, -v28, v30, v27
	v_fmac_f32_e32 v30, v31, v29
	v_sub_f32_e32 v39, v30, v135
	v_cvt_pk_bf16_f32 v34, v36, v37
	v_cvt_pk_bf16_f32 v35, v38, v39
	s_add_u32 s10, s10, 0x2000
	s_addc_u32 s11, s11, 0
	s_nop 0
	global_store_dwordx2 v4, v[34:35], s[10:11] offset:-4096
	s_cmp_gt_u32 s5, 9
	s_cbranch_scc1 .Lp2_ps_8
	v_pk_add_f32 v[24:25], v[24:25], v[196:197] neg_lo:[0,1] neg_hi:[0,1]
	v_pk_add_f32 v[26:27], v[26:27], v[198:199] neg_lo:[0,1] neg_hi:[0,1]
; DI u32x2 pk4(f32x4 v) { u32x2 r; r.x = pk2(v[0], v[1]); r.y = pk2(v[2], v[3]); return r; }
; DI void phase2(CP& p, LAS unsigned char* lds, int wid) {
;     ...
;             for (int i = 0; i < 16; ++i) { const int t = t0 + i, pos = tb + i; const f32x4 zc = *(const f32x4*)(Z + (size_t)t * 1024 + c);
;                 sum += zc; const float cnt = (float)((pos + 1) < win ? (pos + 1) : win); const f32x4 d = sum / cnt - zc;
;                 *(u32x2*)(DP + (size_t)t * 1024 + c) = pk4(d);
;                 if (pos - win + 1 >= 0) sum -= *(const f32x4*)(Z + (size_t)(t - win + 1) * 1024 + c); }
.Lp2_ps_8:
	s_min_u32 s18, s5, 10
	v_cvt_f32_u32_e32 v28, s18
	v_rcp_f32_e32 v29, v28
	v_pk_add_f32 v[24:25], v[24:25], v[136:137]
	v_pk_add_f32 v[26:27], v[26:27], v[138:139]
	v_fma_f32 v30, -v28, v29, 1.0
	v_fmac_f32_e32 v29, v30, v29
	v_mul_f32_e32 v30, v24, v29
	v_fma_f32 v31, -v28, v30, v24
	v_fmac_f32_e32 v30, v31, v29
	v_fma_f32 v31, -v28, v30, v24
	v_fmac_f32_e32 v30, v31, v29
	v_sub_f32_e32 v36, v30, v136
	v_mul_f32_e32 v30, v25, v29
	v_fma_f32 v31, -v28, v30, v25
	v_fmac_f32_e32 v30, v31, v29
	v_fma_f32 v31, -v28, v30, v25
	v_fmac_f32_e32 v30, v31, v29
	v_sub_f32_e32 v37, v30, v137
	v_mul_f32_e32 v30, v26, v29
	v_fma_f32 v31, -v28, v30, v26
	v_fmac_f32_e32 v30, v31, v29
	v_fma_f32 v31, -v28, v30, v26
	v_fmac_f32_e32 v30, v31, v29
	v_sub_f32_e32 v38, v30, v138
	v_mul_f32_e32 v30, v27, v29
	v_fma_f32 v31, -v28, v30, v27
	v_fmac_f32_e32 v30, v31, v29
	v_fma_f32 v31, -v28, v30, v27
	v_fmac_f32_e32 v30, v31, v29
	v_sub_f32_e32 v39, v30, v139
	v_cvt_pk_bf16_f32 v34, v36, v37
	v_cvt_pk_bf16_f32 v35, v38, v39
	s_nop 0
	global_store_dwordx2 v4, v[34:35], s[10:11] offset:-2048
	s_cmp_gt_u32 s5, 10
	s_cbranch_scc1 .Lp2_ps_9
	v_pk_add_f32 v[24:25], v[24:25], v[200:201] neg_lo:[0,1] neg_hi:[0,1]
	v_pk_add_f32 v[26:27], v[26:27], v[202:203] neg_lo:[0,1] neg_hi:[0,1]
.Lp2_ps_9:
	s_min_u32 s18, s5, 11
	v_cvt_f32_u32_e32 v28, s18
	v_rcp_f32_e32 v29, v28
	v_pk_add_f32 v[24:25], v[24:25], v[140:141]
	v_pk_add_f32 v[26:27], v[26:27], v[142:143]
	v_fma_f32 v30, -v28, v29, 1.0
	v_fmac_f32_e32 v29, v30, v29
	v_mul_f32_e32 v30, v24, v29
	v_fma_f32 v31, -v28, v30, v24
	v_fmac_f32_e32 v30, v31, v29
	v_fma_f32 v31, -v28, v30, v24
	v_fmac_f32_e32 v30, v31, v29
	v_sub_f32_e32 v36, v30, v140
	v_mul_f32_e32 v30, v25, v29
	v_fma_f32 v31, -v28, v30, v25
	v_fmac_f32_e32 v30, v31, v29
	v_fma_f32 v31, -v28, v30, v25
	v_fmac_f32_e32 v30, v31, v29
	v_sub_f32_e32 v37, v30, v141
	v_mul_f32_e32 v30, v26, v29
	v_fma_f32 v31, -v28, v30, v26
	v_fmac_f32_e32 v30, v31, v29
	v_fma_f32 v31, -v28, v30, v26
	v_fmac_f32_e32 v30, v31, v29
	v_sub_f32_e32 v38, v30, v142
	v_mul_f32_e32 v30, v27, v29
	v_fma_f32 v31, -v28, v30, v27
	v_fmac_f32_e32 v30, v31, v29
	v_fma_f32 v31, -v28, v30, v27
	v_fmac_f32_e32 v30, v31, v29
	v_sub_f32_e32 v39, v30, v143
	v_cvt_pk_bf16_f32 v34, v36, v37
	v_cvt_pk_bf16_f32 v35, v38, v39
	s_nop 0
	global_store_dwordx2 v4, v[34:35], s[10:11]
	s_cmp_gt_u32 s5, 11
	s_cbranch_scc1 .Lp2_ps_10
	v_pk_add_f32 v[24:25], v[24:25], v[204:205] neg_lo:[0,1] neg_hi:[0,1]
	v_pk_add_f32 v[26:27], v[26:27], v[206:207] neg_lo:[0,1] neg_hi:[0,1]
.Lp2_ps_10:
	s_min_u32 s18, s5, 12
	v_cvt_f32_u32_e32 v28, s18
	v_rcp_f32_e32 v29, v28
	v_pk_add_f32 v[24:25], v[24:25], v[144:145]
	v_pk_add_f32 v[26:27], v[26:27], v[146:147]
	v_fma_f32 v30, -v28, v29, 1.0
	v_fmac_f32_e32 v29, v30, v29
	v_mul_f32_e32 v30, v24, v29
	v_fma_f32 v31, -v28, v30, v24
	v_fmac_f32_e32 v30, v31, v29
	v_fma_f32 v31, -v28, v30, v24
	v_fmac_f32_e32 v30, v31, v29
	v_sub_f32_e32 v36, v30, v144
	v_mul_f32_e32 v30, v25, v29
	v_fma_f32 v31, -v28, v30, v25
	v_fmac_f32_e32 v30, v31, v29
	v_fma_f32 v31, -v28, v30, v25
	v_fmac_f32_e32 v30, v31, v29
	v_sub_f32_e32 v37, v30, v145
	v_mul_f32_e32 v30, v26, v29
	v_fma_f32 v31, -v28, v30, v26
	v_fmac_f32_e32 v30, v31, v29
	v_fma_f32 v31, -v28, v30, v26
	v_fmac_f32_e32 v30, v31, v29
	v_sub_f32_e32 v38, v30, v146
	v_mul_f32_e32 v30, v27, v29
	v_fma_f32 v31, -v28, v30, v27
	v_fmac_f32_e32 v30, v31, v29
	v_fma_f32 v31, -v28, v30, v27
	v_fmac_f32_e32 v30, v31, v29
	v_sub_f32_e32 v39, v30, v147
	v_cvt_pk_bf16_f32 v34, v36, v37
	v_cvt_pk_bf16_f32 v35, v38, v39
	s_nop 0
	global_store_dwordx2 v4, v[34:35], s[10:11] offset:2048
	s_cmp_gt_u32 s5, 12
	s_cbranch_scc1 .Lp2_ps_11
	v_pk_add_f32 v[24:25], v[24:25], v[208:209] neg_lo:[0,1] neg_hi:[0,1]
	v_pk_add_f32 v[26:27], v[26:27], v[210:211] neg_lo:[0,1] neg_hi:[0,1]
.Lp2_ps_11:
	s_min_u32 s18, s5, 13
	v_cvt_f32_u32_e32 v28, s18
	v_rcp_f32_e32 v29, v28
	v_pk_add_f32 v[24:25], v[24:25], v[148:149]
	v_pk_add_f32 v[26:27], v[26:27], v[150:151]
	v_fma_f32 v30, -v28, v29, 1.0
	v_fmac_f32_e32 v29, v30, v29
	v_mul_f32_e32 v30, v24, v29
	v_fma_f32 v31, -v28, v30, v24
	v_fmac_f32_e32 v30, v31, v29
	v_fma_f32 v31, -v28, v30, v24
	v_fmac_f32_e32 v30, v31, v29
	v_sub_f32_e32 v36, v30, v148
	v_mul_f32_e32 v30, v25, v29
	v_fma_f32 v31, -v28, v30, v25
	v_fmac_f32_e32 v30, v31, v29
	v_fma_f32 v31, -v28, v30, v25
	v_fmac_f32_e32 v30, v31, v29
	v_sub_f32_e32 v37, v30, v149
	v_mul_f32_e32 v30, v26, v29
	v_fma_f32 v31, -v28, v30, v26
	v_fmac_f32_e32 v30, v31, v29
	v_fma_f32 v31, -v28, v30, v26
	v_fmac_f32_e32 v30, v31, v29
	v_sub_f32_e32 v38, v30, v150
	v_mul_f32_e32 v30, v27, v29
	v_fma_f32 v31, -v28, v30, v27
	v_fmac_f32_e32 v30, v31, v29
	v_fma_f32 v31, -v28, v30, v27
	v_fmac_f32_e32 v30, v31, v29
	v_sub_f32_e32 v39, v30, v151
	v_cvt_pk_bf16_f32 v34, v36, v37
	v_cvt_pk_bf16_f32 v35, v38, v39
	s_add_u32 s10, s10, 0x2000
	s_addc_u32 s11, s11, 0
	s_nop 0
	global_store_dwordx2 v4, v[34:35], s[10:11] offset:-4096
	s_cmp_gt_u32 s5, 13
	s_cbranch_scc1 .Lp2_ps_12
	v_pk_add_f32 v[24:25], v[24:25], v[212:213] neg_lo:[0,1] neg_hi:[0,1]
	v_pk_add_f32 v[26:27], v[26:27], v[214:215] neg_lo:[0,1] neg_hi:[0,1]
; #define LAS __attribute__((address_space(3)))
; DI unsigned pk2(float a, float b) { f32x2 f = {a, b}; bf16v2 r = __builtin_convertvector(f, bf16v2); return __builtin_bit_cast(unsigned, r); }
; DI u32x2 pk4(f32x4 v) { u32x2 r; r.x = pk2(v[0], v[1]); r.y = pk2(v[2], v[3]); return r; }
; DI float rstd_of(float ssq, float inv_n) { return __builtin_amdgcn_rsqf(ssq * inv_n + 1e-6f); }
; DI void phase2(CP& p, LAS unsigned char* lds, int wid) {
;     ...
;             for (int i = 0; i < 16; ++i) { const int t = t0 + i, pos = tb + i; const f32x4 zc = *(const f32x4*)(Z + (size_t)t * 1024 + c);
;                 sum += zc; const float cnt = (float)((pos + 1) < win ? (pos + 1) : win); const f32x4 d = sum / cnt - zc;
;                 *(u32x2*)(DP + (size_t)t * 1024 + c) = pk4(d);
;                 if (pos - win + 1 >= 0) sum -= *(const f32x4*)(Z + (size_t)(t - win + 1) * 1024 + c); }
;     ...
;             const int item = it - 256, nb = item >> 3, h = item & 7, t0 = nb * 128;
;             if (tid < 128) rsl[tid] = rstd_of(SSQ(1)[t0 + tid], 1.f / 1024.f);
;             __syncthreads();
;             { const int t = tid >> 2, sq = (tid & 3) * 32; const float* wrow = p.w_s + ((size_t)h * 128 + t) * 128 + sq;
; #pragma unroll
;               for (int e = 0; e < 4; ++e) { const f32x4 a = *(const f32x4*)(wrow + e * 8), b = *(const f32x4*)(wrow + e * 8 + 4); const int s0 = sq + e * 8;
;                   const float mk = ((s0 >> 6) <= (t >> 6)) ? 1.f : 0.f;
;                   u32x4 w; w.x = pk2(a[0] * mk * rsl[s0], a[1] * mk * rsl[s0 + 1]); w.y = pk2(a[2] * mk * rsl[s0 + 2], a[3] * mk * rsl[s0 + 3]);
;                   w.z = pk2(b[0] * mk * rsl[s0 + 4], b[1] * mk * rsl[s0 + 5]); w.w = pk2(b[2] * mk * rsl[s0 + 6], b[3] * mk * rsl[s0 + 7]);
;                   *(LAS u32x4*)(wm + t * 272 + s0 * 2) = w; } }
;             __syncthreads();
;             const int ch = h * 128 + 16 * wid + fr; const bf16_t* vt = WSB(OFF_VT) + (size_t)ch * 8192 + t0 + 8 * fq;
;             bf16x8 bfr[4];
; #pragma unroll
;             for (int ks = 0; ks < 4; ++ks) bfr[ks] = *(const bf16x8*)(vt + 32 * ks);
.Lp2_ps_12:
	s_min_u32 s18, s5, 14
	v_cvt_f32_u32_e32 v28, s18
	v_rcp_f32_e32 v29, v28
	v_pk_add_f32 v[24:25], v[24:25], v[152:153]
	v_pk_add_f32 v[26:27], v[26:27], v[154:155]
	v_fma_f32 v30, -v28, v29, 1.0
	v_fmac_f32_e32 v29, v30, v29
	v_mul_f32_e32 v30, v24, v29
	v_fma_f32 v31, -v28, v30, v24
	v_fmac_f32_e32 v30, v31, v29
	v_fma_f32 v31, -v28, v30, v24
	v_fmac_f32_e32 v30, v31, v29
	v_sub_f32_e32 v36, v30, v152
	v_mul_f32_e32 v30, v25, v29
	v_fma_f32 v31, -v28, v30, v25
	v_fmac_f32_e32 v30, v31, v29
	v_fma_f32 v31, -v28, v30, v25
	v_fmac_f32_e32 v30, v31, v29
	v_sub_f32_e32 v37, v30, v153
	v_mul_f32_e32 v30, v26, v29
	v_fma_f32 v31, -v28, v30, v26
	v_fmac_f32_e32 v30, v31, v29
	v_fma_f32 v31, -v28, v30, v26
	v_fmac_f32_e32 v30, v31, v29
	v_sub_f32_e32 v38, v30, v154
	v_mul_f32_e32 v30, v27, v29
	v_fma_f32 v31, -v28, v30, v27
	v_fmac_f32_e32 v30, v31, v29
	v_fma_f32 v31, -v28, v30, v27
	v_fmac_f32_e32 v30, v31, v29
	v_sub_f32_e32 v39, v30, v155
	v_cvt_pk_bf16_f32 v34, v36, v37
	v_cvt_pk_bf16_f32 v35, v38, v39
	s_nop 0
	global_store_dwordx2 v4, v[34:35], s[10:11] offset:-2048
	s_cmp_gt_u32 s5, 14
	s_cbranch_scc1 .Lp2_ps_13
	v_pk_add_f32 v[24:25], v[24:25], v[216:217] neg_lo:[0,1] neg_hi:[0,1]
	v_pk_add_f32 v[26:27], v[26:27], v[218:219] neg_lo:[0,1] neg_hi:[0,1]
.Lp2_ps_13:
	s_min_u32 s18, s5, 15
	v_cvt_f32_u32_e32 v28, s18
	v_rcp_f32_e32 v29, v28
	v_pk_add_f32 v[24:25], v[24:25], v[156:157]
	v_pk_add_f32 v[26:27], v[26:27], v[158:159]
	v_fma_f32 v30, -v28, v29, 1.0
	v_fmac_f32_e32 v29, v30, v29
	v_mul_f32_e32 v30, v24, v29
	v_fma_f32 v31, -v28, v30, v24
	v_fmac_f32_e32 v30, v31, v29
	v_fma_f32 v31, -v28, v30, v24
	v_fmac_f32_e32 v30, v31, v29
	v_sub_f32_e32 v36, v30, v156
	v_mul_f32_e32 v30, v25, v29
	v_fma_f32 v31, -v28, v30, v25
	v_fmac_f32_e32 v30, v31, v29
	v_fma_f32 v31, -v28, v30, v25
	v_fmac_f32_e32 v30, v31, v29
	v_sub_f32_e32 v37, v30, v157
	v_mul_f32_e32 v30, v26, v29
	v_fma_f32 v31, -v28, v30, v26
	v_fmac_f32_e32 v30, v31, v29
	v_fma_f32 v31, -v28, v30, v26
	v_fmac_f32_e32 v30, v31, v29
	v_sub_f32_e32 v38, v30, v158
	v_mul_f32_e32 v30, v27, v29
	v_fma_f32 v31, -v28, v30, v27
	v_fmac_f32_e32 v30, v31, v29
	v_fma_f32 v31, -v28, v30, v27
	v_fmac_f32_e32 v30, v31, v29
	v_sub_f32_e32 v39, v30, v159
	v_cvt_pk_bf16_f32 v34, v36, v37
	v_cvt_pk_bf16_f32 v35, v38, v39
	s_nop 0
	global_store_dwordx2 v4, v[34:35], s[10:11]
	s_cmp_gt_u32 s5, 15
	s_cbranch_scc1 .Lp2_ps_14
	v_pk_add_f32 v[24:25], v[24:25], v[220:221] neg_lo:[0,1] neg_hi:[0,1]
	v_pk_add_f32 v[26:27], v[26:27], v[222:223] neg_lo:[0,1] neg_hi:[0,1]
.Lp2_ps_14:
	s_min_u32 s18, s5, 16
	v_cvt_f32_u32_e32 v28, s18
	v_rcp_f32_e32 v29, v28
	v_pk_add_f32 v[24:25], v[24:25], v[160:161]
	v_pk_add_f32 v[26:27], v[26:27], v[162:163]
	v_fma_f32 v30, -v28, v29, 1.0
	v_fmac_f32_e32 v29, v30, v29
	v_mul_f32_e32 v30, v24, v29
	v_fma_f32 v31, -v28, v30, v24
	v_fmac_f32_e32 v30, v31, v29
	v_fma_f32 v31, -v28, v30, v24
	v_fmac_f32_e32 v30, v31, v29
	v_sub_f32_e32 v36, v30, v160
	v_mul_f32_e32 v30, v25, v29
	v_fma_f32 v31, -v28, v30, v25
	v_fmac_f32_e32 v30, v31, v29
	v_fma_f32 v31, -v28, v30, v25
	v_fmac_f32_e32 v30, v31, v29
	v_sub_f32_e32 v37, v30, v161
	v_mul_f32_e32 v30, v26, v29
	v_fma_f32 v31, -v28, v30, v26
	v_fmac_f32_e32 v30, v31, v29
	v_fma_f32 v31, -v28, v30, v26
	v_fmac_f32_e32 v30, v31, v29
	v_sub_f32_e32 v38, v30, v162
	v_mul_f32_e32 v30, v27, v29
	v_fma_f32 v31, -v28, v30, v27
	v_fmac_f32_e32 v30, v31, v29
	v_fma_f32 v31, -v28, v30, v27
	v_fmac_f32_e32 v30, v31, v29
	v_sub_f32_e32 v39, v30, v163
	v_cvt_pk_bf16_f32 v34, v36, v37
	v_cvt_pk_bf16_f32 v35, v38, v39
	s_nop 0
	global_store_dwordx2 v4, v[34:35], s[10:11] offset:2048
	s_cmp_gt_u32 s5, 16
	s_cbranch_scc1 .Lp2_ps_15
	v_pk_add_f32 v[24:25], v[24:25], v[224:225] neg_lo:[0,1] neg_hi:[0,1]
	v_pk_add_f32 v[26:27], v[26:27], v[226:227] neg_lo:[0,1] neg_hi:[0,1]
.Lp2_ps_15:
	s_branch .Lp2_next
.Lp2_gmlp:
	s_add_i32 s2, s39, 0xffffff00
	s_and_b32 s3, s2, 7
	s_lshr_b32 s2, s2, 3
	s_lshl_b32 s2, s2, 7
	s_lshl_b32 s4, s2, 2
	s_add_u32 s10, s20, s4
	s_addc_u32 s11, s21, 0
	global_load_dword v22, v20, s[10:11]
	s_lshl_b32 s4, s3, 16
	s_add_u32 s10, s14, s4
	s_addc_u32 s11, s15, 0
	global_load_dwordx4 v[100:103], v8, s[10:11]
	global_load_dwordx4 v[104:107], v8, s[10:11] offset:16
	global_load_dwordx4 v[108:111], v8, s[10:11] offset:32
	global_load_dwordx4 v[112:115], v8, s[10:11] offset:48
	global_load_dwordx4 v[116:119], v8, s[10:11] offset:64
	global_load_dwordx4 v[120:123], v8, s[10:11] offset:80
	global_load_dwordx4 v[124:127], v8, s[10:11] offset:96
	global_load_dwordx4 v[128:131], v8, s[10:11] offset:112
	s_lshl_b32 s4, s3, 21
	s_lshl_b32 s5, s2, 1
	s_add_i32 s4, s4, s5
	s_add_u32 s10, s28, s4
	s_addc_u32 s11, s29, 0
	global_load_dwordx4 v[132:135], v14, s[10:11]
	global_load_dwordx4 v[136:139], v14, s[10:11] offset:64
	global_load_dwordx4 v[140:143], v14, s[10:11] offset:128
	global_load_dwordx4 v[144:147], v14, s[10:11] offset:192
	s_lshl_b32 s4, s3, 9
	s_add_u32 s10, s12, s4
	s_addc_u32 s11, s13, 0
	global_load_dwordx4 v[148:151], v15, s[10:11]
	s_add_u32 s10, s22, s4
	s_addc_u32 s11, s23, 0
	global_load_dword v176, v16, s[10:11]
	global_load_dword v178, v16, s[10:11] offset:64
	global_load_dword v180, v16, s[10:11] offset:128
	global_load_dword v182, v16, s[10:11] offset:192
	global_load_dword v184, v16, s[10:11] offset:256
	global_load_dword v186, v16, s[10:11] offset:320
	global_load_dword v188, v16, s[10:11] offset:384
	global_load_dword v190, v16, s[10:11] offset:448
	s_lshl_b32 s4, s2, 11
	s_lshl_b32 s5, s3, 8
	s_add_i32 s4, s4, s5
	s_add_u32 s10, s30, s4
	s_addc_u32 s11, s31, 0
	global_load_dwordx2 v[160:161], v17, s[10:11]
	s_add_u32 s10, s10, 0x8000
	s_addc_u32 s11, s11, 0
	global_load_dwordx2 v[162:163], v17, s[10:11]
	s_add_u32 s10, s10, 0x8000
	s_addc_u32 s11, s11, 0
	global_load_dwordx2 v[164:165], v17, s[10:11]
	s_add_u32 s10, s10, 0x8000
	s_addc_u32 s11, s11, 0
	global_load_dwordx2 v[166:167], v17, s[10:11]
	s_add_u32 s10, s10, 0x8000
	s_addc_u32 s11, s11, 0
	global_load_dwordx2 v[168:169], v17, s[10:11]
	s_add_u32 s10, s10, 0x8000
	s_addc_u32 s11, s11, 0
	global_load_dwordx2 v[170:171], v17, s[10:11]
	s_add_u32 s10, s10, 0x8000
	s_addc_u32 s11, s11, 0
	global_load_dwordx2 v[172:173], v17, s[10:11]
	s_add_u32 s10, s10, 0x8000
	s_addc_u32 s11, s11, 0
	global_load_dwordx2 v[174:175], v17, s[10:11]
	s_lshl_b32 s4, s2, 12
	s_add_i32 s4, s4, s5
	s_add_u32 s18, s36, s4
	s_addc_u32 s19, s37, 0
	s_waitcnt vmcnt(29)
	v_fmamk_f32 v22, v22, 0x3a800000, v23
	v_rsq_f32_e32 v22, v22
	s_nop 0
	ds_write_b32 v21, v22
	s_waitcnt lgkmcnt(0)
	s_barrier
; #define LAS __attribute__((address_space(3)))
; DI unsigned pk2(float a, float b) { f32x2 f = {a, b}; bf16v2 r = __builtin_convertvector(f, bf16v2); return __builtin_bit_cast(unsigned, r); }
; DI void phase2(CP& p, LAS unsigned char* lds, int wid) {
;     ...
;             { const int t = tid >> 2, sq = (tid & 3) * 32; const float* wrow = p.w_s + ((size_t)h * 128 + t) * 128 + sq;
; #pragma unroll
;               for (int e = 0; e < 4; ++e) { const f32x4 a = *(const f32x4*)(wrow + e * 8), b = *(const f32x4*)(wrow + e * 8 + 4); const int s0 = sq + e * 8;
;                   const float mk = ((s0 >> 6) <= (t >> 6)) ? 1.f : 0.f;
;                   u32x4 w; w.x = pk2(a[0] * mk * rsl[s0], a[1] * mk * rsl[s0 + 1]); w.y = pk2(a[2] * mk * rsl[s0 + 2], a[3] * mk * rsl[s0 + 3]);
;                   w.z = pk2(b[0] * mk * rsl[s0 + 4], b[1] * mk * rsl[s0 + 5]); w.w = pk2(b[2] * mk * rsl[s0 + 6], b[3] * mk * rsl[s0 + 7]);
;                   *(LAS u32x4*)(wm + t * 272 + s0 * 2) = w; } }
;             __syncthreads();
;             const int ch = h * 128 + 16 * wid + fr; const bf16_t* vt = WSB(OFF_VT) + (size_t)ch * 8192 + t0 + 8 * fq;
;             bf16x8 bfr[4];
; #pragma unroll
;             for (int ks = 0; ks < 4; ++ks) bfr[ks] = *(const bf16x8*)(vt + 32 * ks);
;             f32x4 acc[8];
; #pragma unroll
;             for (int tt = 0; tt < 8; ++tt) { acc[tt] = (f32x4){0.f, 0.f, 0.f, 0.f};
; #pragma unroll
;                 for (int ks = 0; ks < 4; ++ks) { const bf16x8 af = *(const LAS bf16x8*)(wm + (16 * tt + fr) * 272 + (32 * ks + 8 * fq) * 2);
;                     acc[tt] = __builtin_amdgcn_mfma_f32_16x16x32_bf16(bfr[ks], af, acc[tt], 0, 0, 0); } }
	ds_read_b128 v[24:27], v12
	ds_read_b128 v[28:31], v12 offset:16
	ds_read_b128 v[32:35], v12 offset:32
	ds_read_b128 v[36:39], v12 offset:48
	ds_read_b128 v[40:43], v12 offset:64
	ds_read_b128 v[44:47], v12 offset:80
	ds_read_b128 v[48:51], v12 offset:96
	ds_read_b128 v[52:55], v12 offset:112
	s_waitcnt vmcnt(21)
	s_waitcnt lgkmcnt(7)
	v_pk_mul_f32 v[100:101], v[10:11], v[100:101]
	v_pk_mul_f32 v[102:103], v[10:11], v[102:103]
	v_pk_mul_f32 v[100:101], v[100:101], v[24:25]
	v_pk_mul_f32 v[102:103], v[102:103], v[26:27]
	s_waitcnt lgkmcnt(6)
	v_pk_mul_f32 v[104:105], v[10:11], v[104:105]
	v_pk_mul_f32 v[106:107], v[10:11], v[106:107]
	v_pk_mul_f32 v[104:105], v[104:105], v[28:29]
	v_pk_mul_f32 v[106:107], v[106:107], v[30:31]
	s_waitcnt lgkmcnt(5)
	v_pk_mul_f32 v[108:109], v[10:11], v[108:109]
	v_pk_mul_f32 v[110:111], v[10:11], v[110:111]
	v_pk_mul_f32 v[108:109], v[108:109], v[32:33]
	v_pk_mul_f32 v[110:111], v[110:111], v[34:35]
	s_waitcnt lgkmcnt(4)
	v_pk_mul_f32 v[112:113], v[10:11], v[112:113]
	v_pk_mul_f32 v[114:115], v[10:11], v[114:115]
	v_pk_mul_f32 v[112:113], v[112:113], v[36:37]
	v_pk_mul_f32 v[114:115], v[114:115], v[38:39]
	s_waitcnt lgkmcnt(3)
	v_pk_mul_f32 v[116:117], v[10:11], v[116:117]
	v_pk_mul_f32 v[118:119], v[10:11], v[118:119]
	v_pk_mul_f32 v[116:117], v[116:117], v[40:41]
	v_pk_mul_f32 v[118:119], v[118:119], v[42:43]
	s_waitcnt lgkmcnt(2)
	v_pk_mul_f32 v[120:121], v[10:11], v[120:121]
	v_pk_mul_f32 v[122:123], v[10:11], v[122:123]
	v_pk_mul_f32 v[120:121], v[120:121], v[44:45]
	v_pk_mul_f32 v[122:123], v[122:123], v[46:47]
	s_waitcnt lgkmcnt(1)
	v_pk_mul_f32 v[124:125], v[10:11], v[124:125]
	v_pk_mul_f32 v[126:127], v[10:11], v[126:127]
	v_pk_mul_f32 v[124:125], v[124:125], v[48:49]
	v_pk_mul_f32 v[126:127], v[126:127], v[50:51]
	s_waitcnt lgkmcnt(0)
	v_pk_mul_f32 v[128:129], v[10:11], v[128:129]
	v_pk_mul_f32 v[130:131], v[10:11], v[130:131]
	v_pk_mul_f32 v[128:129], v[128:129], v[52:53]
	v_pk_mul_f32 v[130:131], v[130:131], v[54:55]
	v_cvt_pk_bf16_f32 v24, v100, v101
	v_cvt_pk_bf16_f32 v25, v102, v103
	v_cvt_pk_bf16_f32 v26, v104, v105
	v_cvt_pk_bf16_f32 v27, v106, v107
	v_cvt_pk_bf16_f32 v28, v108, v109
	v_cvt_pk_bf16_f32 v29, v110, v111
	v_cvt_pk_bf16_f32 v30, v112, v113
	v_cvt_pk_bf16_f32 v31, v114, v115
	v_cvt_pk_bf16_f32 v32, v116, v117
	v_cvt_pk_bf16_f32 v33, v118, v119
	v_cvt_pk_bf16_f32 v34, v120, v121
	v_cvt_pk_bf16_f32 v35, v122, v123
	v_cvt_pk_bf16_f32 v36, v124, v125
	v_cvt_pk_bf16_f32 v37, v126, v127
	v_cvt_pk_bf16_f32 v38, v128, v129
	v_cvt_pk_bf16_f32 v39, v130, v131
	s_nop 0
	ds_write_b128 v13, v[24:27]
	ds_write_b128 v13, v[28:31] offset:16
	ds_write_b128 v13, v[32:35] offset:32
	ds_write_b128 v13, v[36:39] offset:48
	s_waitcnt lgkmcnt(0)
	s_barrier
	ds_read_b128 v[24:27], v19 offset:0
	ds_read_b128 v[28:31], v19 offset:64
	ds_read_b128 v[32:35], v19 offset:128
	ds_read_b128 v[36:39], v19 offset:192
	ds_read_b128 v[40:43], v19 offset:4352
	ds_read_b128 v[44:47], v19 offset:4416
	ds_read_b128 v[48:51], v19 offset:4480
	ds_read_b128 v[52:55], v19 offset:4544
	s_waitcnt vmcnt(17)
	s_waitcnt lgkmcnt(7)
	v_mfma_f32_16x16x32_bf16 v[56:59], v[132:135], v[24:27], 0
	s_waitcnt lgkmcnt(6)
	v_mfma_f32_16x16x32_bf16 v[56:59], v[136:139], v[28:31], v[56:59]
	s_waitcnt lgkmcnt(5)
	v_mfma_f32_16x16x32_bf16 v[56:59], v[140:143], v[32:35], v[56:59]
	s_waitcnt lgkmcnt(4)
	v_mfma_f32_16x16x32_bf16 v[56:59], v[144:147], v[36:39], v[56:59]
	ds_read_b128 v[24:27], v19 offset:8704
	ds_read_b128 v[28:31], v19 offset:8768
	ds_read_b128 v[32:35], v19 offset:8832
	ds_read_b128 v[36:39], v19 offset:8896
	s_waitcnt lgkmcnt(7)
	v_mfma_f32_16x16x32_bf16 v[60:63], v[132:135], v[40:43], 0
	s_waitcnt lgkmcnt(6)
	v_mfma_f32_16x16x32_bf16 v[60:63], v[136:139], v[44:47], v[60:63]
	s_waitcnt lgkmcnt(5)
	v_mfma_f32_16x16x32_bf16 v[60:63], v[140:143], v[48:51], v[60:63]
	s_waitcnt lgkmcnt(4)
	v_mfma_f32_16x16x32_bf16 v[60:63], v[144:147], v[52:55], v[60:63]
	ds_read_b128 v[40:43], v19 offset:13056
	ds_read_b128 v[44:47], v19 offset:13120
	ds_read_b128 v[48:51], v19 offset:13184
	ds_read_b128 v[52:55], v19 offset:13248
	s_waitcnt lgkmcnt(7)
	v_mfma_f32_16x16x32_bf16 v[64:67], v[132:135], v[24:27], 0
	s_waitcnt lgkmcnt(6)
	v_mfma_f32_16x16x32_bf16 v[64:67], v[136:139], v[28:31], v[64:67]
	s_waitcnt lgkmcnt(5)
	v_mfma_f32_16x16x32_bf16 v[64:67], v[140:143], v[32:35], v[64:67]
	s_waitcnt lgkmcnt(4)
	v_mfma_f32_16x16x32_bf16 v[64:67], v[144:147], v[36:39], v[64:67]
	ds_read_b128 v[24:27], v19 offset:17408
	ds_read_b128 v[28:31], v19 offset:17472
	ds_read_b128 v[32:35], v19 offset:17536
	ds_read_b128 v[36:39], v19 offset:17600
	s_waitcnt lgkmcnt(7)
	v_mfma_f32_16x16x32_bf16 v[68:71], v[132:135], v[40:43], 0
	s_waitcnt lgkmcnt(6)
	v_mfma_f32_16x16x32_bf16 v[68:71], v[136:139], v[44:47], v[68:71]
	s_waitcnt lgkmcnt(5)
	v_mfma_f32_16x16x32_bf16 v[68:71], v[140:143], v[48:51], v[68:71]
	s_waitcnt lgkmcnt(4)
	v_mfma_f32_16x16x32_bf16 v[68:71], v[144:147], v[52:55], v[68:71]
	ds_read_b128 v[40:43], v19 offset:21760
	ds_read_b128 v[44:47], v19 offset:21824
	ds_read_b128 v[48:51], v19 offset:21888
	ds_read_b128 v[52:55], v19 offset:21952
	s_waitcnt lgkmcnt(7)
	v_mfma_f32_16x16x32_bf16 v[72:75], v[132:135], v[24:27], 0
	s_waitcnt lgkmcnt(6)
	v_mfma_f32_16x16x32_bf16 v[72:75], v[136:139], v[28:31], v[72:75]
	s_waitcnt lgkmcnt(5)
	v_mfma_f32_16x16x32_bf16 v[72:75], v[140:143], v[32:35], v[72:75]
	s_waitcnt lgkmcnt(4)
	v_mfma_f32_16x16x32_bf16 v[72:75], v[144:147], v[36:39], v[72:75]
	ds_read_b128 v[24:27], v19 offset:26112
	ds_read_b128 v[28:31], v19 offset:26176
	ds_read_b128 v[32:35], v19 offset:26240
	ds_read_b128 v[36:39], v19 offset:26304
	s_waitcnt lgkmcnt(7)
; #define LAS __attribute__((address_space(3)))
; DI u32x2 pk4(f32x4 v) { u32x2 r; r.x = pk2(v[0], v[1]); r.y = pk2(v[2], v[3]); return r; }
; DI float bf_lo(unsigned w) { return __uint_as_float(w << 16); }
; DI float bf_hi(unsigned w) { return __uint_as_float(w & 0xffff0000u); }
; DI void phase2(CP& p, LAS unsigned char* lds, int wid) {
;     ...
;             for (int tt = 0; tt < 8; ++tt) { acc[tt] = (f32x4){0.f, 0.f, 0.f, 0.f};
; #pragma unroll
;                 for (int ks = 0; ks < 4; ++ks) { const bf16x8 af = *(const LAS bf16x8*)(wm + (16 * tt + fr) * 272 + (32 * ks + 8 * fq) * 2);
;                     acc[tt] = __builtin_amdgcn_mfma_f32_16x16x32_bf16(bfr[ks], af, acc[tt], 0, 0, 0); } }
;             const int d0 = h * 128 + 16 * wid + 4 * fq; const f32x4 gv = *(const f32x4*)(p.g_v + d0);
; #pragma unroll
;             for (int tt = 0; tt < 8; ++tt) { const int t = 16 * tt + fr, tok = t0 + t; const float bs = p.b_s[h * 128 + t];
;                 const u32x2 uw = *(const u32x2*)(WSB(OFF_U) + (size_t)tok * 1024 + d0);
;                 f32x4 a; a[0] = bf_lo(uw.x) * (acc[tt][0] * gv[0] + bs); a[1] = bf_hi(uw.x) * (acc[tt][1] * gv[1] + bs);
;                 a[2] = bf_lo(uw.y) * (acc[tt][2] * gv[2] + bs); a[3] = bf_hi(uw.y) * (acc[tt][3] * gv[3] + bs);
;                 *(u32x2*)(WSB(OFF_CAT) + (size_t)tok * 2048 + d0) = pk4(a); }
	v_mfma_f32_16x16x32_bf16 v[76:79], v[132:135], v[40:43], 0
	s_waitcnt lgkmcnt(6)
	v_mfma_f32_16x16x32_bf16 v[76:79], v[136:139], v[44:47], v[76:79]
	s_waitcnt lgkmcnt(5)
	v_mfma_f32_16x16x32_bf16 v[76:79], v[140:143], v[48:51], v[76:79]
	s_waitcnt lgkmcnt(4)
	v_mfma_f32_16x16x32_bf16 v[76:79], v[144:147], v[52:55], v[76:79]
	ds_read_b128 v[40:43], v19 offset:30464
	ds_read_b128 v[44:47], v19 offset:30528
	ds_read_b128 v[48:51], v19 offset:30592
	ds_read_b128 v[52:55], v19 offset:30656
	s_waitcnt lgkmcnt(7)
	v_mfma_f32_16x16x32_bf16 v[80:83], v[132:135], v[24:27], 0
	s_waitcnt lgkmcnt(6)
	v_mfma_f32_16x16x32_bf16 v[80:83], v[136:139], v[28:31], v[80:83]
	s_waitcnt lgkmcnt(5)
	v_mfma_f32_16x16x32_bf16 v[80:83], v[140:143], v[32:35], v[80:83]
	s_waitcnt lgkmcnt(4)
	v_mfma_f32_16x16x32_bf16 v[80:83], v[144:147], v[36:39], v[80:83]
	s_waitcnt lgkmcnt(3)
	v_mfma_f32_16x16x32_bf16 v[84:87], v[132:135], v[40:43], 0
	s_waitcnt lgkmcnt(2)
	v_mfma_f32_16x16x32_bf16 v[84:87], v[136:139], v[44:47], v[84:87]
	s_waitcnt lgkmcnt(1)
	v_mfma_f32_16x16x32_bf16 v[84:87], v[140:143], v[48:51], v[84:87]
	s_waitcnt lgkmcnt(0)
	v_mfma_f32_16x16x32_bf16 v[84:87], v[144:147], v[52:55], v[84:87]
	s_waitcnt vmcnt(0)
	s_nop 7
	v_pk_fma_f32 v[56:57], v[56:57], v[148:149], v[176:177] op_sel_hi:[1,1,0]
	v_pk_fma_f32 v[58:59], v[58:59], v[150:151], v[176:177] op_sel_hi:[1,1,0]
	v_lshlrev_b32_e32 v24, 16, v160
	v_and_b32_e32 v25, 0xffff0000, v160
	v_lshlrev_b32_e32 v26, 16, v161
	v_and_b32_e32 v27, 0xffff0000, v161
	v_pk_mul_f32 v[56:57], v[56:57], v[24:25]
	v_pk_mul_f32 v[58:59], v[58:59], v[26:27]
	v_cvt_pk_bf16_f32 v56, v56, v57
	v_cvt_pk_bf16_f32 v57, v58, v59
	global_store_dwordx2 v18, v[56:57], s[18:19]
	v_pk_fma_f32 v[60:61], v[60:61], v[148:149], v[178:179] op_sel_hi:[1,1,0]
	v_pk_fma_f32 v[62:63], v[62:63], v[150:151], v[178:179] op_sel_hi:[1,1,0]
	v_lshlrev_b32_e32 v24, 16, v162
	v_and_b32_e32 v25, 0xffff0000, v162
	v_lshlrev_b32_e32 v26, 16, v163
	v_and_b32_e32 v27, 0xffff0000, v163
	v_pk_mul_f32 v[60:61], v[60:61], v[24:25]
	v_pk_mul_f32 v[62:63], v[62:63], v[26:27]
	v_cvt_pk_bf16_f32 v60, v60, v61
	v_cvt_pk_bf16_f32 v61, v62, v63
	s_add_u32 s18, s18, 0x10000
	s_addc_u32 s19, s19, 0
	global_store_dwordx2 v18, v[60:61], s[18:19]
	v_pk_fma_f32 v[64:65], v[64:65], v[148:149], v[180:181] op_sel_hi:[1,1,0]
	v_pk_fma_f32 v[66:67], v[66:67], v[150:151], v[180:181] op_sel_hi:[1,1,0]
	v_lshlrev_b32_e32 v24, 16, v164
	v_and_b32_e32 v25, 0xffff0000, v164
	v_lshlrev_b32_e32 v26, 16, v165
	v_and_b32_e32 v27, 0xffff0000, v165
	v_pk_mul_f32 v[64:65], v[64:65], v[24:25]
	v_pk_mul_f32 v[66:67], v[66:67], v[26:27]
	v_cvt_pk_bf16_f32 v64, v64, v65
	v_cvt_pk_bf16_f32 v65, v66, v67
	s_add_u32 s18, s18, 0x10000
	s_addc_u32 s19, s19, 0
	global_store_dwordx2 v18, v[64:65], s[18:19]
	v_pk_fma_f32 v[68:69], v[68:69], v[148:149], v[182:183] op_sel_hi:[1,1,0]
	v_pk_fma_f32 v[70:71], v[70:71], v[150:151], v[182:183] op_sel_hi:[1,1,0]
	v_lshlrev_b32_e32 v24, 16, v166
	v_and_b32_e32 v25, 0xffff0000, v166
	v_lshlrev_b32_e32 v26, 16, v167
	v_and_b32_e32 v27, 0xffff0000, v167
	v_pk_mul_f32 v[68:69], v[68:69], v[24:25]
	v_pk_mul_f32 v[70:71], v[70:71], v[26:27]
	v_cvt_pk_bf16_f32 v68, v68, v69
	v_cvt_pk_bf16_f32 v69, v70, v71
	s_add_u32 s18, s18, 0x10000
	s_addc_u32 s19, s19, 0
	global_store_dwordx2 v18, v[68:69], s[18:19]
	v_pk_fma_f32 v[72:73], v[72:73], v[148:149], v[184:185] op_sel_hi:[1,1,0]
	v_pk_fma_f32 v[74:75], v[74:75], v[150:151], v[184:185] op_sel_hi:[1,1,0]
	v_lshlrev_b32_e32 v24, 16, v168
	v_and_b32_e32 v25, 0xffff0000, v168
	v_lshlrev_b32_e32 v26, 16, v169
	v_and_b32_e32 v27, 0xffff0000, v169
	v_pk_mul_f32 v[72:73], v[72:73], v[24:25]
	v_pk_mul_f32 v[74:75], v[74:75], v[26:27]
	v_cvt_pk_bf16_f32 v72, v72, v73
	v_cvt_pk_bf16_f32 v73, v74, v75
	s_add_u32 s18, s18, 0x10000
	s_addc_u32 s19, s19, 0
	global_store_dwordx2 v18, v[72:73], s[18:19]
	v_pk_fma_f32 v[76:77], v[76:77], v[148:149], v[186:187] op_sel_hi:[1,1,0]
	v_pk_fma_f32 v[78:79], v[78:79], v[150:151], v[186:187] op_sel_hi:[1,1,0]
	v_lshlrev_b32_e32 v24, 16, v170
	v_and_b32_e32 v25, 0xffff0000, v170
	v_lshlrev_b32_e32 v26, 16, v171
	v_and_b32_e32 v27, 0xffff0000, v171
	v_pk_mul_f32 v[76:77], v[76:77], v[24:25]
	v_pk_mul_f32 v[78:79], v[78:79], v[26:27]
	v_cvt_pk_bf16_f32 v76, v76, v77
	v_cvt_pk_bf16_f32 v77, v78, v79
	s_add_u32 s18, s18, 0x10000
	s_addc_u32 s19, s19, 0
	global_store_dwordx2 v18, v[76:77], s[18:19]
	v_pk_fma_f32 v[80:81], v[80:81], v[148:149], v[188:189] op_sel_hi:[1,1,0]
	v_pk_fma_f32 v[82:83], v[82:83], v[150:151], v[188:189] op_sel_hi:[1,1,0]
	v_lshlrev_b32_e32 v24, 16, v172
	v_and_b32_e32 v25, 0xffff0000, v172
	v_lshlrev_b32_e32 v26, 16, v173
	v_and_b32_e32 v27, 0xffff0000, v173
	v_pk_mul_f32 v[80:81], v[80:81], v[24:25]
	v_pk_mul_f32 v[82:83], v[82:83], v[26:27]
	v_cvt_pk_bf16_f32 v80, v80, v81
	v_cvt_pk_bf16_f32 v81, v82, v83
	s_add_u32 s18, s18, 0x10000
	s_addc_u32 s19, s19, 0
	global_store_dwordx2 v18, v[80:81], s[18:19]
	v_pk_fma_f32 v[84:85], v[84:85], v[148:149], v[190:191] op_sel_hi:[1,1,0]
	v_pk_fma_f32 v[86:87], v[86:87], v[150:151], v[190:191] op_sel_hi:[1,1,0]
	v_lshlrev_b32_e32 v24, 16, v174
	v_and_b32_e32 v25, 0xffff0000, v174
	v_lshlrev_b32_e32 v26, 16, v175
	v_and_b32_e32 v27, 0xffff0000, v175
	v_pk_mul_f32 v[84:85], v[84:85], v[24:25]
	v_pk_mul_f32 v[86:87], v[86:87], v[26:27]
	v_cvt_pk_bf16_f32 v84, v84, v85
	v_cvt_pk_bf16_f32 v85, v86, v87
	s_add_u32 s18, s18, 0x10000
	s_addc_u32 s19, s19, 0
	global_store_dwordx2 v18, v[84:85], s[18:19]
.Lp2_next:
	s_add_i32 s39, s39, s7
	s_cmpk_lt_i32 s39, 0x300
	s_cbranch_scc1 .Lp2_item
